# prompt attention key-block loop: K and V fragment LDS reads issued 6 deep through spare registers with counted lgkmcnt (were read+wait+mfma chains); plus earlier scan/cprep/epilogue edits
# speedup vs baseline: 1.0058x; 1.0017x over previous
; #define LAS __attribute__((address_space(3)))
; __device__ __forceinline__ unsigned pk2(float lo, float hi) { const f32x2 v = {lo, hi}; const bf16x2_t b = __builtin_convertvector(v, bf16x2_t); return __builtin_bit_cast(unsigned, b); }
; __device__ __forceinline__ void attn_unit(Frame& F, int b, int h, int qt, int kb_lo, int nkb, const bf16* QB, const bf16* KB, const bf16* VT, bf16* OUT, float bias2, f32x4* part, float* tpart) {
;     ...
;             const float Y3 = carry, Y2 = Y3 * GT[3], Y1 = Y2 * GT[2], Y0 = Y1 * GT[1];
;             carry = Y0 * GT[0];
;             const float f[4] = {Y0 * X[0], Y1 * X[1], Y2 * X[2], Y3 * X[3]};
;             bf16x8 pf[2];
; #pragma unroll
;             for (int ks = 0; ks < 2; ++ks) { u32x4 pw; pw.x = pk2(bt[2 * ks][0] * f[2 * ks], bt[2 * ks][1] * f[2 * ks]); pw.y = pk2(bt[2 * ks][2] * f[2 * ks], bt[2 * ks][3] * f[2 * ks]);
;                 pw.z = pk2(bt[2 * ks + 1][0] * f[2 * ks + 1], bt[2 * ks + 1][1] * f[2 * ks + 1]); pw.w = pk2(bt[2 * ks + 1][2] * f[2 * ks + 1], bt[2 * ks + 1][3] * f[2 * ks + 1]); pf[ks] = __builtin_bit_cast(bf16x8, pw); }
; #pragma unroll
;             for (int dt = 0; dt < 8; ++dt)
; #pragma unroll
;                 for (int ks = 0; ks < 2; ++ks) { const LAS bf16* vp = Vb + (16 * dt + li) * 72 + 32 * ks + 4 * g;
;                     const u32x2 a0 = *(const LAS u32x2*)vp, a1 = *(const LAS u32x2*)(vp + 16); const u32x4 av = (u32x4){a0.x, a0.y, a1.x, a1.y};
;                     oacc[dt] = __builtin_amdgcn_mfma_f32_16x16x32_bf16(__builtin_bit_cast(bf16x8, av), pf[ks], oacc[dt], 0, 0, 0); }
.LBB0_1058:
	s_or_b64 exec, exec, s[4:5]
	s_waitcnt lgkmcnt(5)
	v_mul_f32_e32 v137, v140, v141
	v_pk_mul_f32 v[140:141], v[104:105], v[100:101]
	s_waitcnt lgkmcnt(2)
	v_mul_f32_e32 v101, v102, v131
	s_waitcnt lgkmcnt(1)
	v_mul_f32_e32 v101, v101, v135
	v_mul_f32_e32 v137, v137, v142
	v_mul_f32_e32 v100, v133, v134
	s_waitcnt lgkmcnt(0)
	v_mul_f32_e32 v101, v101, v136
	v_mul_f32_e32 v137, v137, v143
	v_mul_f32_e32 v100, v100, v138
	v_mul_f32_e32 v101, v81, v101
	v_mul_f32_e32 v100, v100, v139
	v_mul_f32_e32 v102, v137, v101
	v_pk_mul_f32 v[92:93], v[108:109], v[92:93]
	v_mul_f32_e32 v109, v100, v102
	v_mul_f32_e32 v88, v127, v88
	v_pk_mul_f32 v[86:87], v[110:111], v[86:87]
	s_mul_i32 s4, s27, 0x4800
	v_mul_f32_e32 v100, v116, v109
	v_mul_f32_e32 v104, v117, v102
	v_mul_f32_e32 v108, v81, v103
	v_pk_mul_f32 v[86:87], v[86:87], v[100:101] op_sel_hi:[1,0]
	v_pk_mul_f32 v[88:89], v[88:89], v[100:101] op_sel_hi:[1,0]
	v_add3_u32 v81, v77, s4, v73
	v_add_u32_e32 v183, 0x8800, v81
	v_add_u32_e32 v164, 0x9000, v81
	v_add_u32_e32 v165, 0x9800, v81
	v_add_u32_e32 v166, 0xa000, v81
	v_add_u32_e32 v167, 0xa800, v81
	v_add_u32_e32 v168, 0xb000, v81
	v_add_u32_e32 v169, 0xb800, v81
	v_add_u32_e32 v182, 0xc000, v81
	ds_read2_b64 v[184:187], v183 offset1:4
	ds_read2_b64 v[188:191], v183 offset0:8 offset1:12
	ds_read2_b64 v[192:195], v164 offset0:32 offset1:36
	ds_read2_b64 v[196:199], v164 offset0:40 offset1:44
	ds_read2_b64 v[200:203], v165 offset0:64 offset1:68
	ds_read2_b64 v[204:207], v165 offset0:72 offset1:76
	v_cvt_pk_bf16_f32 v86, v86, v87
	v_cvt_pk_bf16_f32 v87, v88, v89
	v_pk_mul_f32 v[88:89], v[92:93], v[104:105] op_sel_hi:[1,0]
	v_pk_mul_f32 v[96:97], v[106:107], v[96:97]
	v_mul_f32_e32 v106, v132, v101
	v_mul_f32_e32 v90, v128, v90
	v_pk_mul_f32 v[90:91], v[90:91], v[104:105] op_sel_hi:[1,0]
	v_cvt_pk_bf16_f32 v88, v88, v89
	v_cvt_pk_bf16_f32 v89, v90, v91
	v_mul_f32_e32 v94, v129, v94
	v_pk_mul_f32 v[94:95], v[94:95], v[106:107] op_sel_hi:[1,0]
	s_nop 0
	s_waitcnt lgkmcnt(5)
	v_mfma_f32_16x16x32_bf16 v[30:33], v[184:187], v[86:89], v[30:33]
	ds_read2_b64 v[184:187], v166 offset0:96 offset1:100
	v_mul_f32_e32 v98, v130, v98
	v_cvt_pk_bf16_f32 v105, v94, v95
	v_pk_mul_f32 v[94:95], v[140:141], v[108:109] op_sel_hi:[1,0]
	v_pk_mul_f32 v[96:97], v[96:97], v[106:107] op_sel_hi:[1,0]
	v_cvt_pk_bf16_f32 v106, v94, v95
	v_pk_mul_f32 v[94:95], v[98:99], v[108:109] op_sel_hi:[1,0]
	v_cvt_pk_bf16_f32 v104, v96, v97
	v_cvt_pk_bf16_f32 v107, v94, v95
	s_nop 1
	s_waitcnt lgkmcnt(5)
	v_mfma_f32_16x16x32_bf16 v[30:33], v[188:191], v[104:107], v[30:33]
	ds_read2_b64 v[188:191], v166 offset0:104 offset1:108
	s_waitcnt lgkmcnt(5)
	v_mfma_f32_16x16x32_bf16 v[26:29], v[192:195], v[86:89], v[26:29]
	ds_read2_b64 v[192:195], v167 offset0:128 offset1:132
	s_waitcnt lgkmcnt(5)
	v_mfma_f32_16x16x32_bf16 v[26:29], v[196:199], v[104:107], v[26:29]
	ds_read2_b64 v[196:199], v167 offset0:136 offset1:140
	s_waitcnt lgkmcnt(5)
	v_mfma_f32_16x16x32_bf16 v[22:25], v[200:203], v[86:89], v[22:25]
	ds_read2_b64 v[200:203], v168 offset0:160 offset1:164
	s_waitcnt lgkmcnt(5)
	v_mfma_f32_16x16x32_bf16 v[22:25], v[204:207], v[104:107], v[22:25]
	ds_read2_b64 v[204:207], v168 offset0:168 offset1:172
	s_waitcnt lgkmcnt(5)
	v_mfma_f32_16x16x32_bf16 v[18:21], v[184:187], v[86:89], v[18:21]
	ds_read2_b64 v[184:187], v169 offset0:192 offset1:196
	s_waitcnt lgkmcnt(5)
	v_mfma_f32_16x16x32_bf16 v[18:21], v[188:191], v[104:107], v[18:21]
	ds_read2_b64 v[188:191], v169 offset0:200 offset1:204
	s_waitcnt lgkmcnt(5)
	v_mfma_f32_16x16x32_bf16 v[14:17], v[192:195], v[86:89], v[14:17]
	ds_read2_b64 v[192:195], v182 offset0:224 offset1:228
	s_waitcnt lgkmcnt(5)
	v_mfma_f32_16x16x32_bf16 v[14:17], v[196:199], v[104:107], v[14:17]
	ds_read2_b64 v[196:199], v182 offset0:232 offset1:236
	s_waitcnt lgkmcnt(5)
	v_mfma_f32_16x16x32_bf16 v[10:13], v[200:203], v[86:89], v[10:13]
	s_waitcnt lgkmcnt(4)
	v_mfma_f32_16x16x32_bf16 v[10:13], v[204:207], v[104:107], v[10:13]
	s_waitcnt lgkmcnt(3)
	v_mfma_f32_16x16x32_bf16 v[6:9], v[184:187], v[86:89], v[6:9]
	s_waitcnt lgkmcnt(2)
	v_mfma_f32_16x16x32_bf16 v[6:9], v[188:191], v[104:107], v[6:9]
	v_mul_f32_e32 v81, v112, v113
	v_mul_f32_e32 v81, v81, v114
	s_waitcnt lgkmcnt(1)
	v_mfma_f32_16x16x32_bf16 v[2:5], v[192:195], v[86:89], v[2:5]
	v_mul_f32_e32 v81, v81, v115
	v_mul_f32_e32 v81, v81, v109
	s_waitcnt lgkmcnt(0)
	v_mfma_f32_16x16x32_bf16 v[2:5], v[196:199], v[104:107], v[2:5]

; #define LAS __attribute__((address_space(3)))
; __device__ __forceinline__ float ex2(float x) { return __builtin_amdgcn_exp2f(x); }
; __device__ __forceinline__ float rcpf_(float x) { return __builtin_amdgcn_rcpf(x); }
; __device__ __forceinline__ void attn_unit(Frame& F, int b, int h, int qt, int kb_lo, int nkb, const bf16* QB, const bf16* KB, const bf16* VT, bf16* OUT, float bias2, f32x4* part, float* tpart) {
;     ...
;         if (more) { const int k2 = kb - 1;
;             lk[0] = *(const u32x4*)(kg + (size_t)(k2 * 64 + kr0) * BW); lk[1] = *(const u32x4*)(kg + (size_t)(k2 * 64 + kr0 + 32) * BW);
;             lv[0] = *(const u32x4*)(vg + (size_t)vr0 * SEQ + k2 * 64); lv[1] = *(const u32x4*)(vg + (size_t)(vr0 + 64) * SEQ + k2 * 64); }
;         if (kb * 64 < q0 + 15) {
;             const LAS bf16* Kb = Ks + buf * (64 * 136); const LAS bf16* Vb = Vs + buf * (128 * 72);
;             f32x4 s[4];
; #pragma unroll
;             for (int st = 0; st < 4; ++st) { s[st] = (f32x4){bias2, bias2, bias2, bias2};
; #pragma unroll
;                 for (int ks = 0; ks < 4; ++ks) { const bf16x8 af = *(const LAS bf16x8*)(Kb + (16 * st + li) * 136 + 32 * ks + 8 * g); s[st] = __builtin_amdgcn_mfma_f32_16x16x32_bf16(af, qf[ks], s[st], 0, 0, 0); } }
;             float om[4][4], bt[4][4], lt[4], X[4], GT[4];
;             if (kb * 64 + 63 >= q0) {
;                 const int kbase = kb * 64 + 4 * g;
; #pragma unroll
;                 for (int st = 0; st < 4; ++st)
; #pragma unroll
;                     for (int r = 0; r < 4; ++r) { const float e = ex2(s[st][r]); float o = rcpf_(1.0f + e), bb = e * o;
;                         if (kbase + 16 * st + r >= qpos) { o = 1.f; bb = 0.f; }
;                         om[st][r] = o; bt[st][r] = bb; }
;             } else {
; #pragma unroll
;                 for (int st = 0; st < 4; ++st)
; #pragma unroll
;                     for (int r = 0; r < 4; ++r) { const float e = ex2(s[st][r]); const float o = rcpf_(1.0f + e); om[st][r] = o; bt[st][r] = e * o; }
.LBB0_1060:
	v_add_u32_e32 v58, s26, v119
	s_add_i32 s2, s26, 0xffffff81
	v_add_u32_e32 v56, 0xffffff81, v58
	v_add_u32_e32 v58, 0xffffffa1, v58
	v_ashrrev_i32_e32 v57, 31, v56
	v_ashrrev_i32_e32 v59, 31, v58
	s_ashr_i32 s3, s2, 31
	v_lshlrev_b64 v[56:57], 10, v[56:57]
	v_lshlrev_b64 v[58:59], 10, v[58:59]
	s_lshl_b64 s[2:3], s[2:3], 1
	v_lshl_add_u64 v[56:57], v[78:79], 0, v[56:57]
	v_lshl_add_u64 v[60:61], v[78:79], 0, v[58:59]
	v_lshl_add_u64 v[64:65], v[82:83], 0, s[2:3]
	v_lshl_add_u64 v[68:69], v[84:85], 0, s[2:3]
	global_load_dwordx4 v[56:59], v[56:57], off
	s_nop 0
	global_load_dwordx4 v[60:63], v[60:61], off
	s_nop 0
	global_load_dwordx4 v[64:67], v[64:65], off
	s_nop 0
	global_load_dwordx4 v[68:71], v[68:69], off
	s_sub_i32 s2, s26, 63
	s_and_b32 s27, s24, 1
	v_cmp_lt_i32_e64 s[4:5], s2, v124
	s_and_saveexec_b64 s[2:3], s[4:5]
	s_cbranch_execz .LBB0_1059
	s_mul_i32 s4, s27, 0x4400
	v_add3_u32 v106, v120, s4, v121
	ds_read_b128 v[184:187], v106
	ds_read_b128 v[188:191], v106 offset:64
	ds_read_b128 v[192:195], v106 offset:128
	ds_read_b128 v[196:199], v106 offset:192
	ds_read_b128 v[200:203], v106 offset:4352
	ds_read_b128 v[204:207], v106 offset:4416
	v_cmp_ge_i32_e64 s[4:5], s26, v118
	s_waitcnt vmcnt(4) lgkmcnt(5)
	v_mfma_f32_16x16x32_bf16 v[86:89], v[184:187], v[48:51], v[52:55]
	ds_read_b128 v[184:187], v106 offset:4480
	s_waitcnt lgkmcnt(5)
	v_mfma_f32_16x16x32_bf16 v[86:89], v[188:191], v[44:47], v[86:89]
	ds_read_b128 v[188:191], v106 offset:4544
	s_waitcnt lgkmcnt(5)
	v_mfma_f32_16x16x32_bf16 v[86:89], v[192:195], v[40:43], v[86:89]
	ds_read_b128 v[192:195], v106 offset:8704
	s_waitcnt lgkmcnt(5)
	v_mfma_f32_16x16x32_bf16 v[86:89], v[196:199], v[36:39], v[86:89]
	ds_read_b128 v[196:199], v106 offset:8768
	s_waitcnt lgkmcnt(5)
	v_mfma_f32_16x16x32_bf16 v[90:93], v[200:203], v[48:51], v[52:55]
	ds_read_b128 v[200:203], v106 offset:8832
	s_waitcnt lgkmcnt(5)
	v_mfma_f32_16x16x32_bf16 v[90:93], v[204:207], v[44:47], v[90:93]
	ds_read_b128 v[204:207], v106 offset:8896
	s_waitcnt lgkmcnt(5)
	v_mfma_f32_16x16x32_bf16 v[90:93], v[184:187], v[40:43], v[90:93]
	ds_read_b128 v[184:187], v106 offset:13056
	v_exp_f32_e32 v116, v86
	v_exp_f32_e32 v117, v87
	v_exp_f32_e32 v150, v88
	s_waitcnt lgkmcnt(5)
	v_mfma_f32_16x16x32_bf16 v[90:93], v[188:191], v[36:39], v[90:93]
	ds_read_b128 v[188:191], v106 offset:13120
	v_exp_f32_e32 v149, v89
	v_add_f32_e32 v157, 1.0, v116
	v_add_f32_e32 v158, 1.0, v117
	s_waitcnt lgkmcnt(5)
	v_mfma_f32_16x16x32_bf16 v[94:97], v[192:195], v[48:51], v[52:55]
	ds_read_b128 v[192:195], v106 offset:13184
	v_add_f32_e32 v156, 1.0, v150
	v_add_f32_e32 v155, 1.0, v149
	s_waitcnt lgkmcnt(5)
	v_mfma_f32_16x16x32_bf16 v[94:97], v[196:199], v[44:47], v[94:97]
	ds_read_b128 v[196:199], v106 offset:13248
	s_waitcnt lgkmcnt(5)
	v_mfma_f32_16x16x32_bf16 v[94:97], v[200:203], v[40:43], v[94:97]
	v_exp_f32_e32 v114, v90
	v_exp_f32_e32 v115, v91
	v_exp_f32_e32 v144, v92
	s_waitcnt lgkmcnt(4)
	v_mfma_f32_16x16x32_bf16 v[94:97], v[204:207], v[36:39], v[94:97]
	v_exp_f32_e32 v141, v93
	v_add_f32_e32 v153, 1.0, v114
	v_add_f32_e32 v154, 1.0, v115
	s_waitcnt lgkmcnt(3)
	v_mfma_f32_16x16x32_bf16 v[98:101], v[184:187], v[48:51], v[52:55]
	v_add_f32_e32 v152, 1.0, v144
	v_add_f32_e32 v151, 1.0, v141
	s_waitcnt lgkmcnt(2)
	v_mfma_f32_16x16x32_bf16 v[98:101], v[188:191], v[44:47], v[98:101]
	s_waitcnt lgkmcnt(1)
	v_mfma_f32_16x16x32_bf16 v[98:101], v[192:195], v[40:43], v[98:101]
	v_exp_f32_e32 v112, v94
	v_exp_f32_e32 v113, v95
	v_exp_f32_e32 v140, v96
	s_waitcnt lgkmcnt(0)
	v_mfma_f32_16x16x32_bf16 v[98:101], v[196:199], v[36:39], v[98:101]
	v_exp_f32_e32 v137, v97
	v_add_f32_e32 v147, 1.0, v112
	v_add_f32_e32 v148, 1.0, v113
	v_add_f32_e32 v146, 1.0, v140
	v_add_f32_e32 v145, 1.0, v137
	s_nop 7
	v_exp_f32_e32 v110, v98
	v_exp_f32_e32 v111, v99
	v_exp_f32_e32 v136, v100
	v_exp_f32_e32 v135, v101
	v_add_f32_e32 v142, 1.0, v110
	v_add_f32_e32 v143, 1.0, v111
	v_add_f32_e32 v139, 1.0, v136
	v_add_f32_e32 v138, 1.0, v135
	s_and_saveexec_b64 s[6:7], s[4:5]
	s_xor_b64 s[16:17], exec, s[6:7]
	s_cbranch_execz .LBB0_1063
; __device__ __forceinline__ float ex2(float x) { return __builtin_amdgcn_exp2f(x); }
; __device__ __forceinline__ float rcpf_(float x) { return __builtin_amdgcn_rcpf(x); }
; __device__ __forceinline__ void attn_unit(Frame& F, int b, int h, int qt, int kb_lo, int nkb, const bf16* QB, const bf16* KB, const bf16* VT, bf16* OUT, float bias2, f32x4* part, float* tpart) {
;     ...
;             if (kb * 64 + 63 >= q0) {
;                 const int kbase = kb * 64 + 4 * g;
; #pragma unroll
;                 for (int st = 0; st < 4; ++st)
; #pragma unroll
;                     for (int r = 0; r < 4; ++r) { const float e = ex2(s[st][r]); float o = rcpf_(1.0f + e), bb = e * o;
;                         if (kbase + 16 * st + r >= qpos) { o = 1.f; bb = 0.f; }
;                         om[st][r] = o; bt[st][r] = bb; }
	v_rcp_f32_e32 v88, v157
	v_rcp_f32_e32 v89, v158
	v_add_u32_e32 v130, s26, v72
	v_subrev_u32_e32 v91, 62, v130
	v_cmp_lt_i32_e64 s[4:5], v91, v1
	v_rcp_f32_e32 v91, v156
	v_rcp_f32_e32 v92, v155
	v_subrev_u32_e32 v90, 63, v130
	v_pk_mul_f32 v[86:87], v[116:117], v[88:89]
	v_cndmask_b32_e64 v109, 1.0, v89, s[4:5]
	v_subrev_u32_e32 v89, 61, v130
	v_cndmask_b32_e64 v87, 0, v87, s[4:5]
	v_cmp_lt_i32_e64 s[6:7], v90, v76
	v_cmp_lt_i32_e64 s[4:5], v89, v76
	v_subrev_u32_e32 v93, 60, v130
	v_cndmask_b32_e64 v108, 1.0, v88, s[6:7]
	v_mul_f32_e32 v88, v150, v91
	v_cndmask_b32_e64 v134, 1.0, v91, s[4:5]
	v_rcp_f32_e32 v90, v153
	v_rcp_f32_e32 v91, v154
	v_cndmask_b32_e64 v88, 0, v88, s[4:5]
	v_mul_f32_e32 v89, v149, v92
	v_cmp_lt_i32_e64 s[4:5], v93, v76
	v_subrev_u32_e32 v94, 46, v130
	v_rcp_f32_e32 v96, v151
	v_cndmask_b32_e64 v89, 0, v89, s[4:5]
	v_cndmask_b32_e64 v127, 1.0, v92, s[4:5]
	v_cmp_lt_i32_e64 s[4:5], v94, v1
	v_rcp_f32_e32 v94, v152
	v_pk_mul_f32 v[92:93], v[114:115], v[90:91]
	v_subrev_u32_e32 v95, 47, v130
	v_cndmask_b32_e64 v107, 1.0, v91, s[4:5]
	v_subrev_u32_e32 v91, 45, v130
	v_cndmask_b32_e64 v86, 0, v86, s[6:7]
	v_cndmask_b32_e64 v93, 0, v93, s[4:5]
	v_cmp_lt_i32_e64 s[6:7], v95, v76
	v_cmp_lt_i32_e64 s[4:5], v91, v76
	v_subrev_u32_e32 v97, 44, v130
	v_cndmask_b32_e64 v106, 1.0, v90, s[6:7]
	v_mul_f32_e32 v90, v144, v94
	v_cndmask_b32_e64 v133, 1.0, v94, s[4:5]
	v_rcp_f32_e32 v94, v147
	v_rcp_f32_e32 v95, v148
	v_cndmask_b32_e64 v90, 0, v90, s[4:5]
	v_mul_f32_e32 v91, v141, v96
	v_cmp_lt_i32_e64 s[4:5], v97, v76
	v_subrev_u32_e32 v98, 30, v130
	v_subrev_u32_e32 v99, 31, v130
	v_cndmask_b32_e64 v91, 0, v91, s[4:5]
	v_cndmask_b32_e64 v128, 1.0, v96, s[4:5]
	v_cmp_lt_i32_e64 s[4:5], v98, v1
	v_rcp_f32_e32 v98, v146
	v_pk_mul_f32 v[96:97], v[112:113], v[94:95]
	v_cndmask_b32_e64 v105, 1.0, v95, s[4:5]
	v_subrev_u32_e32 v95, 29, v130
	v_cndmask_b32_e64 v92, 0, v92, s[6:7]
	v_cndmask_b32_e64 v97, 0, v97, s[4:5]
	v_cmp_lt_i32_e64 s[6:7], v99, v76
	v_cmp_lt_i32_e64 s[4:5], v95, v76
	v_rcp_f32_e32 v100, v145
	v_cndmask_b32_e64 v104, 1.0, v94, s[6:7]
	v_mul_f32_e32 v94, v140, v98
	v_cndmask_b32_e64 v132, 1.0, v98, s[4:5]
	v_rcp_f32_e32 v98, v142
	v_rcp_f32_e32 v99, v143
	v_subrev_u32_e32 v101, 28, v130
	v_cndmask_b32_e64 v94, 0, v94, s[4:5]
	v_cmp_lt_i32_e64 s[4:5], v101, v76
	v_mul_f32_e32 v95, v137, v100
	v_add_u32_e32 v102, -14, v130
	v_cndmask_b32_e64 v129, 1.0, v100, s[4:5]
	v_pk_mul_f32 v[100:101], v[110:111], v[98:99]
	v_rcp_f32_e32 v110, v139
	v_cndmask_b32_e64 v95, 0, v95, s[4:5]
	v_add_u32_e32 v103, -15, v130
	v_cmp_lt_i32_e64 s[4:5], v102, v1
	v_rcp_f32_e32 v111, v138
	v_cndmask_b32_e64 v96, 0, v96, s[6:7]
	v_cmp_lt_i32_e64 s[6:7], v103, v76
	v_cndmask_b32_e64 v103, 1.0, v99, s[4:5]
	v_add_u32_e32 v99, -13, v130
	v_cndmask_b32_e64 v101, 0, v101, s[4:5]
	v_cmp_lt_i32_e64 s[4:5], v99, v76
	v_cndmask_b32_e64 v102, 1.0, v98, s[6:7]
	v_mul_f32_e32 v98, v136, v110
	v_cndmask_b32_e64 v131, 1.0, v110, s[4:5]
	v_add_u32_e32 v110, -12, v130
	v_cndmask_b32_e64 v98, 0, v98, s[4:5]
	v_mul_f32_e32 v99, v135, v111
	v_cmp_lt_i32_e64 s[4:5], v110, v76
	v_cndmask_b32_e64 v100, 0, v100, s[6:7]
	s_nop 0
	v_cndmask_b32_e64 v99, 0, v99, s[4:5]
	v_cndmask_b32_e64 v130, 1.0, v111, s[4:5]
